# stack1 + weight-conversion item loops: 16 global loads in flight per item (inner 2-trip loop unrolled, counted vmcnt)
# baseline (speedup 1.0000x reference)
.LBB0_27:
	v_lshl_add_u64 v[42:43], v[32:33], 0, s[2:3]
	v_lshl_add_u64 v[104:105], v[30:31], 0, s[2:3]
	v_lshl_add_u64 v[106:107], v[28:29], 0, s[2:3]
	v_lshl_add_u64 v[108:109], v[26:27], 0, s[2:3]
	v_lshl_add_u64 v[110:111], v[6:7], 0, s[2:3]
	v_lshl_add_u64 v[112:113], v[4:5], 0, s[2:3]
	v_lshl_add_u64 v[114:115], v[2:3], 0, s[2:3]
	v_lshl_add_u64 v[116:117], v[0:1], 0, s[2:3]
	global_load_dwordx4 v[34:37], v[42:43], off
	global_load_dwordx4 v[38:41], v[104:105], off
	global_load_dwordx4 v[80:83], v[106:107], off
	global_load_dwordx4 v[84:87], v[108:109], off
	global_load_dwordx4 v[88:91], v[110:111], off
	global_load_dwordx4 v[92:95], v[112:113], off
	global_load_dwordx4 v[96:99], v[114:115], off
	global_load_dwordx4 v[100:103], v[116:117], off
	s_add_u32 s2, s2, 0x40000
	s_addc_u32 s3, s3, 0
	v_lshl_add_u64 v[42:43], v[32:33], 0, s[2:3]
	v_lshl_add_u64 v[104:105], v[30:31], 0, s[2:3]
	v_lshl_add_u64 v[106:107], v[28:29], 0, s[2:3]
	v_lshl_add_u64 v[108:109], v[26:27], 0, s[2:3]
	v_lshl_add_u64 v[110:111], v[6:7], 0, s[2:3]
	v_lshl_add_u64 v[112:113], v[4:5], 0, s[2:3]
	v_lshl_add_u64 v[114:115], v[2:3], 0, s[2:3]
	v_lshl_add_u64 v[116:117], v[0:1], 0, s[2:3]
	global_load_dwordx4 v[120:123], v[42:43], off
	global_load_dwordx4 v[124:127], v[104:105], off
	global_load_dwordx4 v[128:131], v[106:107], off
	global_load_dwordx4 v[132:135], v[108:109], off
	global_load_dwordx4 v[136:139], v[110:111], off
	global_load_dwordx4 v[140:143], v[112:113], off
	global_load_dwordx4 v[144:147], v[114:115], off
	global_load_dwordx4 v[148:151], v[116:117], off
	v_add_u32_e32 v42, 0x410, v12
	v_add_u32_e32 v43, 0x418, v12
	v_add_u32_e32 v104, 0x820, v12
	v_add_u32_e32 v105, 0x828, v12
	v_add_u32_e32 v106, 0xc30, v12
	v_add_u32_e32 v107, 0xc38, v12
	v_add_u32_e32 v108, 0x1040, v12
	v_add_u32_e32 v109, 0x1048, v12
	v_add_u32_e32 v110, 0x1450, v12
	v_add_u32_e32 v111, 0x1458, v12
	v_add_u32_e32 v112, 0x1860, v12
	v_add_u32_e32 v113, 0x1868, v12
	v_add_u32_e32 v114, 0x1c70, v12
	v_add_u32_e32 v115, 0x1c78, v12
	s_waitcnt vmcnt(15)
	ds_write2_b32 v12, v34, v35 offset1:1
	ds_write2_b32 v12, v36, v37 offset0:2 offset1:3
	s_waitcnt vmcnt(14)
	ds_write2_b32 v42, v38, v39 offset1:1
	ds_write2_b32 v43, v40, v41 offset1:1
	s_waitcnt vmcnt(13)
	ds_write2_b32 v104, v80, v81 offset1:1
	ds_write2_b32 v105, v82, v83 offset1:1
	s_waitcnt vmcnt(12)
	ds_write2_b32 v106, v84, v85 offset1:1
	ds_write2_b32 v107, v86, v87 offset1:1
	s_waitcnt vmcnt(11)
	ds_write2_b32 v108, v88, v89 offset1:1
	ds_write2_b32 v109, v90, v91 offset1:1
	s_waitcnt vmcnt(10)
	ds_write2_b32 v110, v92, v93 offset1:1
	ds_write2_b32 v111, v94, v95 offset1:1
	s_waitcnt vmcnt(9)
	ds_write2_b32 v112, v96, v97 offset1:1
	ds_write2_b32 v113, v98, v99 offset1:1
	s_waitcnt vmcnt(8)
	ds_write2_b32 v114, v100, v101 offset1:1
	ds_write2_b32 v115, v102, v103 offset1:1
	v_add_u32_e32 v12, 0x2080, v12
	v_add_u32_e32 v42, 0x410, v12
	v_add_u32_e32 v43, 0x418, v12
	v_add_u32_e32 v104, 0x820, v12
	v_add_u32_e32 v105, 0x828, v12
	v_add_u32_e32 v106, 0xc30, v12
	v_add_u32_e32 v107, 0xc38, v12
	v_add_u32_e32 v108, 0x1040, v12
	v_add_u32_e32 v109, 0x1048, v12
	v_add_u32_e32 v110, 0x1450, v12
	v_add_u32_e32 v111, 0x1458, v12
	v_add_u32_e32 v112, 0x1860, v12
	v_add_u32_e32 v113, 0x1868, v12
	v_add_u32_e32 v114, 0x1c70, v12
	v_add_u32_e32 v115, 0x1c78, v12
	s_waitcnt vmcnt(7)
	ds_write2_b32 v12, v120, v121 offset1:1
	ds_write2_b32 v12, v122, v123 offset0:2 offset1:3
	s_waitcnt vmcnt(6)
	ds_write2_b32 v42, v124, v125 offset1:1
	ds_write2_b32 v43, v126, v127 offset1:1
	s_waitcnt vmcnt(5)
	ds_write2_b32 v104, v128, v129 offset1:1
	ds_write2_b32 v105, v130, v131 offset1:1
	s_waitcnt vmcnt(4)
	ds_write2_b32 v106, v132, v133 offset1:1
	ds_write2_b32 v107, v134, v135 offset1:1
	s_waitcnt vmcnt(3)
	ds_write2_b32 v108, v136, v137 offset1:1
	ds_write2_b32 v109, v138, v139 offset1:1
	s_waitcnt vmcnt(2)
	ds_write2_b32 v110, v140, v141 offset1:1
	ds_write2_b32 v111, v142, v143 offset1:1
	s_waitcnt vmcnt(1)
	ds_write2_b32 v112, v144, v145 offset1:1
	ds_write2_b32 v113, v146, v147 offset1:1
	s_waitcnt vmcnt(0)
	ds_write2_b32 v114, v148, v149 offset1:1
	ds_write2_b32 v115, v150, v151 offset1:1
	v_add_u32_e32 v12, 0x2080, v12
	s_add_u32 s2, s2, 0x40000
	s_addc_u32 s3, s3, 0
	s_waitcnt lgkmcnt(0)
	ds_read2_b32 v[6:7], v46 offset1:8
	ds_read2_b32 v[26:27], v46 offset0:65 offset1:73
	ds_read2_b32 v[28:29], v46 offset0:130 offset1:138
	ds_read2_b32 v[30:31], v46 offset0:195 offset1:203
	v_add_u32_e32 v42, 0x400, v46
	s_waitcnt lgkmcnt(3)
	v_bfe_u32 v2, v6, 16, 1
	v_add3_u32 v2, v6, v2, s40
	s_waitcnt lgkmcnt(2)
	v_bfe_u32 v3, v26, 16, 1
	ds_read2_b32 v[32:33], v42 offset0:4 offset1:12
	v_lshrrev_b32_e32 v2, 16, v2
	v_add3_u32 v3, v26, v3, s40
	ds_read2_b32 v[34:35], v42 offset0:69 offset1:77
	v_and_or_b32 v2, v3, s41, v2
	s_waitcnt lgkmcnt(3)
	v_bfe_u32 v3, v28, 16, 1
	v_add3_u32 v3, v28, v3, s40
	s_waitcnt lgkmcnt(2)
	v_bfe_u32 v4, v30, 16, 1
	ds_read2_b32 v[36:37], v42 offset0:134 offset1:142
	v_lshrrev_b32_e32 v3, 16, v3
	v_add3_u32 v4, v30, v4, s40
	ds_read2_b32 v[38:39], v42 offset0:199 offset1:207
	v_and_or_b32 v3, v4, s41, v3
	s_waitcnt lgkmcnt(3)
	v_bfe_u32 v4, v32, 16, 1
	v_add3_u32 v4, v32, v4, s40
	s_waitcnt lgkmcnt(2)
	v_bfe_u32 v5, v34, 16, 1
	v_lshrrev_b32_e32 v4, 16, v4
	v_add3_u32 v5, v34, v5, s40
	v_and_or_b32 v4, v5, s41, v4
	s_waitcnt lgkmcnt(1)
	v_bfe_u32 v5, v36, 16, 1
	s_lshl_b32 s2, s27, 6
	s_lshl_b32 s3, s27, 1
	v_add3_u32 v5, v36, v5, s40
	s_waitcnt lgkmcnt(0)
	v_bfe_u32 v6, v38, 16, 1
	s_and_b32 s2, s2, 0x7c0
	s_and_b32 s3, s3, 0x7fffffc0
	v_lshrrev_b32_e32 v5, 16, v5
	v_add3_u32 v6, v38, v6, s40
	s_add_i32 s18, s3, 0xffffa600
	v_and_or_b32 v5, v6, s41, v5
	v_or_b32_e32 v6, s2, v45
	v_lshl_add_u64 v[0:1], s[18:19], 1, v[14:15]
	v_lshlrev_b32_e32 v12, 12, v6
	v_lshl_add_u64 v[40:41], v[0:1], 0, v[12:13]
	global_store_dwordx4 v[40:41], v[2:5], off
	v_bfe_u32 v6, v39, 16, 1
	v_or_b32_e32 v12, s2, v47
	v_bfe_u32 v2, v7, 16, 1
	v_add3_u32 v2, v7, v2, s40
	v_bfe_u32 v3, v27, 16, 1
	v_lshrrev_b32_e32 v2, 16, v2
	v_add3_u32 v3, v27, v3, s40
	v_and_or_b32 v2, v3, s41, v2
	v_bfe_u32 v3, v29, 16, 1
	v_add3_u32 v3, v29, v3, s40
	v_bfe_u32 v4, v31, 16, 1
	v_lshrrev_b32_e32 v3, 16, v3
	v_add3_u32 v4, v31, v4, s40
	v_and_or_b32 v3, v4, s41, v3
	v_bfe_u32 v4, v33, 16, 1
	v_add3_u32 v4, v33, v4, s40
	v_bfe_u32 v5, v35, 16, 1
	v_lshrrev_b32_e32 v4, 16, v4
	v_add3_u32 v5, v35, v5, s40
	v_and_or_b32 v4, v5, s41, v4
	v_bfe_u32 v5, v37, 16, 1
	v_add3_u32 v5, v37, v5, s40
	v_lshrrev_b32_e32 v5, 16, v5
	v_add3_u32 v6, v39, v6, s40
	v_lshlrev_b32_e32 v12, 12, v12
	v_and_or_b32 v5, v6, s41, v5
	ds_read2_b32 v[6:7], v46 offset0:16 offset1:24
	v_lshl_add_u64 v[26:27], v[0:1], 0, v[12:13]
	global_store_dwordx4 v[26:27], v[2:5], off
	ds_read2_b32 v[26:27], v46 offset0:81 offset1:89
	ds_read2_b32 v[28:29], v46 offset0:146 offset1:154
	ds_read2_b32 v[30:31], v46 offset0:211 offset1:219
	s_waitcnt lgkmcnt(3)
	v_bfe_u32 v2, v6, 16, 1
	v_add3_u32 v2, v6, v2, s40
	s_waitcnt lgkmcnt(2)
	v_bfe_u32 v3, v26, 16, 1
	ds_read2_b32 v[32:33], v42 offset0:20 offset1:28
	v_lshrrev_b32_e32 v2, 16, v2
	v_add3_u32 v3, v26, v3, s40
	ds_read2_b32 v[34:35], v42 offset0:85 offset1:93
	v_and_or_b32 v2, v3, s41, v2
	s_waitcnt lgkmcnt(3)
	v_bfe_u32 v3, v28, 16, 1
	v_add3_u32 v3, v28, v3, s40
	s_waitcnt lgkmcnt(2)
	v_bfe_u32 v4, v30, 16, 1
	ds_read2_b32 v[36:37], v42 offset0:150 offset1:158
	v_lshrrev_b32_e32 v3, 16, v3
	v_add3_u32 v4, v30, v4, s40
	ds_read2_b32 v[38:39], v42 offset0:215 offset1:223
	v_and_or_b32 v3, v4, s41, v3
	s_waitcnt lgkmcnt(3)
	v_bfe_u32 v4, v32, 16, 1
	v_add3_u32 v4, v32, v4, s40
	s_waitcnt lgkmcnt(2)
	v_bfe_u32 v5, v34, 16, 1
	v_lshrrev_b32_e32 v4, 16, v4
	v_add3_u32 v5, v34, v5, s40
	v_and_or_b32 v4, v5, s41, v4
	s_waitcnt lgkmcnt(1)
	v_bfe_u32 v5, v36, 16, 1
	v_add3_u32 v5, v36, v5, s40
	s_waitcnt lgkmcnt(0)
	v_bfe_u32 v6, v38, 16, 1
	v_lshrrev_b32_e32 v5, 16, v5
	v_add3_u32 v6, v38, v6, s40
	v_and_or_b32 v5, v6, s41, v5
	v_or_b32_e32 v6, s2, v48
	v_lshlrev_b32_e32 v12, 12, v6
	v_lshl_add_u64 v[40:41], v[0:1], 0, v[12:13]
	global_store_dwordx4 v[40:41], v[2:5], off
	v_bfe_u32 v6, v39, 16, 1
	v_or_b32_e32 v12, s2, v49
	v_bfe_u32 v2, v7, 16, 1
	v_add3_u32 v2, v7, v2, s40
	v_bfe_u32 v3, v27, 16, 1
	v_lshrrev_b32_e32 v2, 16, v2
	v_add3_u32 v3, v27, v3, s40
	v_and_or_b32 v2, v3, s41, v2
	v_bfe_u32 v3, v29, 16, 1
	v_add3_u32 v3, v29, v3, s40
	v_bfe_u32 v4, v31, 16, 1
	v_lshrrev_b32_e32 v3, 16, v3
	v_add3_u32 v4, v31, v4, s40
	v_and_or_b32 v3, v4, s41, v3
	v_bfe_u32 v4, v33, 16, 1
	v_add3_u32 v4, v33, v4, s40
	v_bfe_u32 v5, v35, 16, 1
	v_lshrrev_b32_e32 v4, 16, v4
	v_add3_u32 v5, v35, v5, s40
	v_and_or_b32 v4, v5, s41, v4
	v_bfe_u32 v5, v37, 16, 1
	v_add3_u32 v5, v37, v5, s40
	v_lshrrev_b32_e32 v5, 16, v5
	v_add3_u32 v6, v39, v6, s40
	v_lshlrev_b32_e32 v12, 12, v12
	v_and_or_b32 v5, v6, s41, v5
	ds_read2_b32 v[6:7], v46 offset0:32 offset1:40
	v_lshl_add_u64 v[26:27], v[0:1], 0, v[12:13]
	global_store_dwordx4 v[26:27], v[2:5], off
	ds_read2_b32 v[26:27], v46 offset0:97 offset1:105
	ds_read2_b32 v[28:29], v46 offset0:162 offset1:170
	ds_read2_b32 v[30:31], v46 offset0:227 offset1:235
	s_waitcnt lgkmcnt(3)
	v_bfe_u32 v2, v6, 16, 1
	v_add3_u32 v2, v6, v2, s40
	s_waitcnt lgkmcnt(2)
	v_bfe_u32 v3, v26, 16, 1
	ds_read2_b32 v[32:33], v42 offset0:36 offset1:44
	v_lshrrev_b32_e32 v2, 16, v2
	v_add3_u32 v3, v26, v3, s40
	ds_read2_b32 v[34:35], v42 offset0:101 offset1:109
	v_and_or_b32 v2, v3, s41, v2
	s_waitcnt lgkmcnt(3)
	v_bfe_u32 v3, v28, 16, 1
	v_add3_u32 v3, v28, v3, s40
	s_waitcnt lgkmcnt(2)
	v_bfe_u32 v4, v30, 16, 1
	ds_read2_b32 v[36:37], v42 offset0:166 offset1:174
	v_lshrrev_b32_e32 v3, 16, v3
	v_add3_u32 v4, v30, v4, s40
	ds_read2_b32 v[38:39], v42 offset0:231 offset1:239
	v_and_or_b32 v3, v4, s41, v3
	s_waitcnt lgkmcnt(3)
	v_bfe_u32 v4, v32, 16, 1
	v_add3_u32 v4, v32, v4, s40
	s_waitcnt lgkmcnt(2)
	v_bfe_u32 v5, v34, 16, 1
	v_lshrrev_b32_e32 v4, 16, v4
	v_add3_u32 v5, v34, v5, s40
	v_and_or_b32 v4, v5, s41, v4
	s_waitcnt lgkmcnt(1)
	v_bfe_u32 v5, v36, 16, 1
	v_add3_u32 v5, v36, v5, s40
	s_waitcnt lgkmcnt(0)
	v_bfe_u32 v6, v38, 16, 1
	v_lshrrev_b32_e32 v5, 16, v5
	v_add3_u32 v6, v38, v6, s40
	v_and_or_b32 v5, v6, s41, v5
	v_or_b32_e32 v6, s2, v50
	v_lshlrev_b32_e32 v12, 12, v6
	v_lshl_add_u64 v[40:41], v[0:1], 0, v[12:13]
	global_store_dwordx4 v[40:41], v[2:5], off
	v_bfe_u32 v6, v39, 16, 1
	v_or_b32_e32 v12, s2, v51
	v_bfe_u32 v2, v7, 16, 1
	v_add3_u32 v2, v7, v2, s40
	v_bfe_u32 v3, v27, 16, 1
	v_lshrrev_b32_e32 v2, 16, v2
	v_add3_u32 v3, v27, v3, s40
	v_and_or_b32 v2, v3, s41, v2
	v_bfe_u32 v3, v29, 16, 1
	v_add3_u32 v3, v29, v3, s40
	v_bfe_u32 v4, v31, 16, 1
	v_lshrrev_b32_e32 v3, 16, v3
	v_add3_u32 v4, v31, v4, s40
	v_and_or_b32 v3, v4, s41, v3
	v_bfe_u32 v4, v33, 16, 1
	v_add3_u32 v4, v33, v4, s40
	v_bfe_u32 v5, v35, 16, 1
	v_lshrrev_b32_e32 v4, 16, v4
	v_add3_u32 v5, v35, v5, s40
	v_and_or_b32 v4, v5, s41, v4
	v_bfe_u32 v5, v37, 16, 1
	v_add3_u32 v5, v37, v5, s40
	v_lshrrev_b32_e32 v5, 16, v5
	v_add3_u32 v6, v39, v6, s40
	v_lshlrev_b32_e32 v12, 12, v12
	v_and_or_b32 v5, v6, s41, v5
	ds_read2_b32 v[6:7], v46 offset0:48 offset1:56
	v_lshl_add_u64 v[26:27], v[0:1], 0, v[12:13]
	global_store_dwordx4 v[26:27], v[2:5], off
	ds_read2_b32 v[26:27], v46 offset0:113 offset1:121
	ds_read2_b32 v[28:29], v46 offset0:178 offset1:186
	ds_read2_b32 v[30:31], v46 offset0:243 offset1:251
	s_waitcnt lgkmcnt(3)
	v_bfe_u32 v2, v6, 16, 1
	v_add3_u32 v2, v6, v2, s40
	s_waitcnt lgkmcnt(2)
	v_bfe_u32 v3, v26, 16, 1
	ds_read2_b32 v[32:33], v42 offset0:52 offset1:60
	v_lshrrev_b32_e32 v2, 16, v2
	v_add3_u32 v3, v26, v3, s40
	ds_read2_b32 v[34:35], v42 offset0:117 offset1:125
	v_and_or_b32 v2, v3, s41, v2
	s_waitcnt lgkmcnt(3)
	v_bfe_u32 v3, v28, 16, 1
	v_add3_u32 v3, v28, v3, s40
	s_waitcnt lgkmcnt(2)
	v_bfe_u32 v4, v30, 16, 1
	ds_read2_b32 v[36:37], v42 offset0:182 offset1:190
	v_lshrrev_b32_e32 v3, 16, v3
	v_add3_u32 v4, v30, v4, s40
	ds_read2_b32 v[38:39], v42 offset0:247 offset1:255
	v_and_or_b32 v3, v4, s41, v3
	s_waitcnt lgkmcnt(3)
	v_bfe_u32 v4, v32, 16, 1
	v_add3_u32 v4, v32, v4, s40
	s_waitcnt lgkmcnt(2)
	v_bfe_u32 v5, v34, 16, 1
	v_lshrrev_b32_e32 v4, 16, v4
	v_add3_u32 v5, v34, v5, s40
	v_and_or_b32 v4, v5, s41, v4
	s_waitcnt lgkmcnt(1)
	v_bfe_u32 v5, v36, 16, 1
	v_add3_u32 v5, v36, v5, s40
	s_waitcnt lgkmcnt(0)
	v_bfe_u32 v6, v38, 16, 1
	v_lshrrev_b32_e32 v5, 16, v5
	v_add3_u32 v6, v38, v6, s40
	v_and_or_b32 v5, v6, s41, v5
	v_or_b32_e32 v6, s2, v52
	v_lshlrev_b32_e32 v12, 12, v6
	v_lshl_add_u64 v[40:41], v[0:1], 0, v[12:13]
	global_store_dwordx4 v[40:41], v[2:5], off
	v_bfe_u32 v6, v39, 16, 1
	v_add3_u32 v6, v39, v6, s40
	v_bfe_u32 v2, v7, 16, 1
	v_add3_u32 v2, v7, v2, s40
	v_bfe_u32 v3, v27, 16, 1
	v_lshrrev_b32_e32 v2, 16, v2
	v_add3_u32 v3, v27, v3, s40
	v_and_or_b32 v2, v3, s41, v2
	v_bfe_u32 v3, v29, 16, 1
	v_add3_u32 v3, v29, v3, s40
	v_bfe_u32 v4, v31, 16, 1
	v_lshrrev_b32_e32 v3, 16, v3
	v_add3_u32 v4, v31, v4, s40
	v_and_or_b32 v3, v4, s41, v3
	v_bfe_u32 v4, v33, 16, 1
	v_add3_u32 v4, v33, v4, s40
	v_bfe_u32 v5, v35, 16, 1
	v_lshrrev_b32_e32 v4, 16, v4
	v_add3_u32 v5, v35, v5, s40
	v_and_or_b32 v4, v5, s41, v4
	v_bfe_u32 v5, v37, 16, 1
	v_add3_u32 v5, v37, v5, s40
	v_lshrrev_b32_e32 v5, 16, v5
	v_and_or_b32 v5, v6, s41, v5
	v_or_b32_e32 v6, s2, v53
	v_lshlrev_b32_e32 v12, 12, v6
	v_lshl_add_u64 v[0:1], v[0:1], 0, v[12:13]
	global_store_dwordx4 v[0:1], v[2:5], off
	s_waitcnt lgkmcnt(0)
	s_mov_b64 s[2:3], 0

.LBB0_53:
	v_lshl_add_u64 v[42:43], v[32:33], 0, s[2:3]
	v_lshl_add_u64 v[104:105], v[30:31], 0, s[2:3]
	v_lshl_add_u64 v[106:107], v[28:29], 0, s[2:3]
	v_lshl_add_u64 v[108:109], v[26:27], 0, s[2:3]
	v_lshl_add_u64 v[110:111], v[6:7], 0, s[2:3]
	v_lshl_add_u64 v[112:113], v[4:5], 0, s[2:3]
	v_lshl_add_u64 v[114:115], v[2:3], 0, s[2:3]
	v_lshl_add_u64 v[116:117], v[0:1], 0, s[2:3]
	global_load_dwordx4 v[34:37], v[42:43], off
	global_load_dwordx4 v[38:41], v[104:105], off
	global_load_dwordx4 v[80:83], v[106:107], off
	global_load_dwordx4 v[84:87], v[108:109], off
	global_load_dwordx4 v[88:91], v[110:111], off
	global_load_dwordx4 v[92:95], v[112:113], off
	global_load_dwordx4 v[96:99], v[114:115], off
	global_load_dwordx4 v[100:103], v[116:117], off
	s_add_u32 s2, s2, 0x40000
	s_addc_u32 s3, s3, 0
	v_lshl_add_u64 v[42:43], v[32:33], 0, s[2:3]
	v_lshl_add_u64 v[104:105], v[30:31], 0, s[2:3]
	v_lshl_add_u64 v[106:107], v[28:29], 0, s[2:3]
	v_lshl_add_u64 v[108:109], v[26:27], 0, s[2:3]
	v_lshl_add_u64 v[110:111], v[6:7], 0, s[2:3]
	v_lshl_add_u64 v[112:113], v[4:5], 0, s[2:3]
	v_lshl_add_u64 v[114:115], v[2:3], 0, s[2:3]
	v_lshl_add_u64 v[116:117], v[0:1], 0, s[2:3]
	global_load_dwordx4 v[120:123], v[42:43], off
	global_load_dwordx4 v[124:127], v[104:105], off
	global_load_dwordx4 v[128:131], v[106:107], off
	global_load_dwordx4 v[132:135], v[108:109], off
	global_load_dwordx4 v[136:139], v[110:111], off
	global_load_dwordx4 v[140:143], v[112:113], off
	global_load_dwordx4 v[144:147], v[114:115], off
	global_load_dwordx4 v[148:151], v[116:117], off
	v_add_u32_e32 v42, 0x410, v12
	v_add_u32_e32 v43, 0x418, v12
	v_add_u32_e32 v79, 0x820, v12
	v_add_u32_e32 v104, 0x828, v12
	v_add_u32_e32 v105, 0xc30, v12
	v_add_u32_e32 v106, 0xc38, v12
	v_add_u32_e32 v107, 0x1040, v12
	v_add_u32_e32 v108, 0x1048, v12
	v_add_u32_e32 v109, 0x1450, v12
	v_add_u32_e32 v110, 0x1458, v12
	v_add_u32_e32 v111, 0x1860, v12
	v_add_u32_e32 v112, 0x1868, v12
	v_add_u32_e32 v113, 0x1c70, v12
	v_add_u32_e32 v114, 0x1c78, v12
	s_waitcnt vmcnt(15)
	ds_write2_b32 v12, v34, v35 offset1:1
	ds_write2_b32 v12, v36, v37 offset0:2 offset1:3
	s_waitcnt vmcnt(14)
	ds_write2_b32 v42, v38, v39 offset1:1
	ds_write2_b32 v43, v40, v41 offset1:1
	s_waitcnt vmcnt(13)
	ds_write2_b32 v79, v80, v81 offset1:1
	ds_write2_b32 v104, v82, v83 offset1:1
	s_waitcnt vmcnt(12)
	ds_write2_b32 v105, v84, v85 offset1:1
	ds_write2_b32 v106, v86, v87 offset1:1
	s_waitcnt vmcnt(11)
	ds_write2_b32 v107, v88, v89 offset1:1
	ds_write2_b32 v108, v90, v91 offset1:1
	s_waitcnt vmcnt(10)
	ds_write2_b32 v109, v92, v93 offset1:1
	ds_write2_b32 v110, v94, v95 offset1:1
	s_waitcnt vmcnt(9)
	ds_write2_b32 v111, v96, v97 offset1:1
	ds_write2_b32 v112, v98, v99 offset1:1
	s_waitcnt vmcnt(8)
	ds_write2_b32 v113, v100, v101 offset1:1
	ds_write2_b32 v114, v102, v103 offset1:1
	v_add_u32_e32 v12, 0x2080, v12
	v_add_u32_e32 v42, 0x410, v12
	v_add_u32_e32 v43, 0x418, v12
	v_add_u32_e32 v79, 0x820, v12
	v_add_u32_e32 v104, 0x828, v12
	v_add_u32_e32 v105, 0xc30, v12
	v_add_u32_e32 v106, 0xc38, v12
	v_add_u32_e32 v107, 0x1040, v12
	v_add_u32_e32 v108, 0x1048, v12
	v_add_u32_e32 v109, 0x1450, v12
	v_add_u32_e32 v110, 0x1458, v12
	v_add_u32_e32 v111, 0x1860, v12
	v_add_u32_e32 v112, 0x1868, v12
	v_add_u32_e32 v113, 0x1c70, v12
	v_add_u32_e32 v114, 0x1c78, v12
	s_waitcnt vmcnt(7)
	ds_write2_b32 v12, v120, v121 offset1:1
	ds_write2_b32 v12, v122, v123 offset0:2 offset1:3
	s_waitcnt vmcnt(6)
	ds_write2_b32 v42, v124, v125 offset1:1
	ds_write2_b32 v43, v126, v127 offset1:1
	s_waitcnt vmcnt(5)
	ds_write2_b32 v79, v128, v129 offset1:1
	ds_write2_b32 v104, v130, v131 offset1:1
	s_waitcnt vmcnt(4)
	ds_write2_b32 v105, v132, v133 offset1:1
	ds_write2_b32 v106, v134, v135 offset1:1
	s_waitcnt vmcnt(3)
	ds_write2_b32 v107, v136, v137 offset1:1
	ds_write2_b32 v108, v138, v139 offset1:1
	s_waitcnt vmcnt(2)
	ds_write2_b32 v109, v140, v141 offset1:1
	ds_write2_b32 v110, v142, v143 offset1:1
	s_waitcnt vmcnt(1)
	ds_write2_b32 v111, v144, v145 offset1:1
	ds_write2_b32 v112, v146, v147 offset1:1
	s_waitcnt vmcnt(0)
	ds_write2_b32 v113, v148, v149 offset1:1
	ds_write2_b32 v114, v150, v151 offset1:1
	v_add_u32_e32 v12, 0x2080, v12
	s_add_u32 s2, s2, 0x40000
	s_addc_u32 s3, s3, 0
	s_waitcnt lgkmcnt(0)
	ds_read2_b32 v[6:7], v46 offset1:8
	ds_read2_b32 v[26:27], v46 offset0:65 offset1:73
	ds_read2_b32 v[28:29], v46 offset0:130 offset1:138
	ds_read2_b32 v[30:31], v46 offset0:195 offset1:203
	v_add_u32_e32 v42, 0x400, v46
	s_waitcnt lgkmcnt(3)
	v_bfe_u32 v2, v6, 16, 1
	v_add3_u32 v2, v6, v2, s40
	s_waitcnt lgkmcnt(2)
	v_bfe_u32 v3, v26, 16, 1
	ds_read2_b32 v[32:33], v42 offset0:4 offset1:12
	v_lshrrev_b32_e32 v2, 16, v2
	v_add3_u32 v3, v26, v3, s40
	ds_read2_b32 v[34:35], v42 offset0:69 offset1:77
	v_and_or_b32 v2, v3, s41, v2
	s_waitcnt lgkmcnt(3)
	v_bfe_u32 v3, v28, 16, 1
	v_add3_u32 v3, v28, v3, s40
	s_waitcnt lgkmcnt(2)
	v_bfe_u32 v4, v30, 16, 1
	ds_read2_b32 v[36:37], v42 offset0:134 offset1:142
	v_lshrrev_b32_e32 v3, 16, v3
	v_add3_u32 v4, v30, v4, s40
	ds_read2_b32 v[38:39], v42 offset0:199 offset1:207
	v_and_or_b32 v3, v4, s41, v3
	s_waitcnt lgkmcnt(3)
	v_bfe_u32 v4, v32, 16, 1
	v_add3_u32 v4, v32, v4, s40
	s_waitcnt lgkmcnt(2)
	v_bfe_u32 v5, v34, 16, 1
	v_lshrrev_b32_e32 v4, 16, v4
	v_add3_u32 v5, v34, v5, s40
	v_and_or_b32 v4, v5, s41, v4
	s_waitcnt lgkmcnt(1)
	v_bfe_u32 v5, v36, 16, 1
	s_lshl_b32 s2, s27, 6
	v_add3_u32 v5, v36, v5, s40
	s_waitcnt lgkmcnt(0)
	v_bfe_u32 v6, v38, 16, 1
	s_and_b32 s2, s2, 0x7c0
	s_lshl_b32 s3, s27, 1
	v_lshrrev_b32_e32 v5, 16, v5
	v_add3_u32 v6, v38, v6, s40
	s_and_b32 s3, s3, 0x7fffffc0
	v_and_or_b32 v5, v6, s41, v5
	v_or_b32_e32 v6, s2, v45
	s_add_i32 s18, s3, 0xffffd400
	v_mul_u32_u24_e32 v6, 0x1600, v6
	v_lshl_add_u64 v[0:1], s[18:19], 1, v[18:19]
	v_lshlrev_b32_e32 v12, 1, v6
	v_lshl_add_u64 v[40:41], v[0:1], 0, v[12:13]
	global_store_dwordx4 v[40:41], v[2:5], off
	v_bfe_u32 v6, v39, 16, 1
	v_add3_u32 v6, v39, v6, s40
	v_bfe_u32 v2, v7, 16, 1
	v_add3_u32 v2, v7, v2, s40
	v_bfe_u32 v3, v27, 16, 1
	v_lshrrev_b32_e32 v2, 16, v2
	v_add3_u32 v3, v27, v3, s40
	v_and_or_b32 v2, v3, s41, v2
	v_bfe_u32 v3, v29, 16, 1
	v_add3_u32 v3, v29, v3, s40
	v_bfe_u32 v4, v31, 16, 1
	v_lshrrev_b32_e32 v3, 16, v3
	v_add3_u32 v4, v31, v4, s40
	v_and_or_b32 v3, v4, s41, v3
	v_bfe_u32 v4, v33, 16, 1
	v_add3_u32 v4, v33, v4, s40
	v_bfe_u32 v5, v35, 16, 1
	v_lshrrev_b32_e32 v4, 16, v4
	v_add3_u32 v5, v35, v5, s40
	v_and_or_b32 v4, v5, s41, v4
	v_bfe_u32 v5, v37, 16, 1
	v_add3_u32 v5, v37, v5, s40
	v_lshrrev_b32_e32 v5, 16, v5
	v_and_or_b32 v5, v6, s41, v5
	v_or_b32_e32 v6, s2, v47
	v_mul_u32_u24_e32 v12, 0x1600, v6
	v_lshlrev_b32_e32 v12, 1, v12
	ds_read2_b32 v[6:7], v46 offset0:16 offset1:24
	v_lshl_add_u64 v[26:27], v[0:1], 0, v[12:13]
	global_store_dwordx4 v[26:27], v[2:5], off
	ds_read2_b32 v[26:27], v46 offset0:81 offset1:89
	ds_read2_b32 v[28:29], v46 offset0:146 offset1:154
	ds_read2_b32 v[30:31], v46 offset0:211 offset1:219
	s_waitcnt lgkmcnt(3)
	v_bfe_u32 v2, v6, 16, 1
	v_add3_u32 v2, v6, v2, s40
	s_waitcnt lgkmcnt(2)
	v_bfe_u32 v3, v26, 16, 1
	ds_read2_b32 v[32:33], v42 offset0:20 offset1:28
	v_lshrrev_b32_e32 v2, 16, v2
	v_add3_u32 v3, v26, v3, s40
	ds_read2_b32 v[34:35], v42 offset0:85 offset1:93
	v_and_or_b32 v2, v3, s41, v2
	s_waitcnt lgkmcnt(3)
	v_bfe_u32 v3, v28, 16, 1
	v_add3_u32 v3, v28, v3, s40
	s_waitcnt lgkmcnt(2)
	v_bfe_u32 v4, v30, 16, 1
	ds_read2_b32 v[36:37], v42 offset0:150 offset1:158
	v_lshrrev_b32_e32 v3, 16, v3
	v_add3_u32 v4, v30, v4, s40
	ds_read2_b32 v[38:39], v42 offset0:215 offset1:223
	v_and_or_b32 v3, v4, s41, v3
	s_waitcnt lgkmcnt(3)
	v_bfe_u32 v4, v32, 16, 1
	v_add3_u32 v4, v32, v4, s40
	s_waitcnt lgkmcnt(2)
	v_bfe_u32 v5, v34, 16, 1
	v_lshrrev_b32_e32 v4, 16, v4
	v_add3_u32 v5, v34, v5, s40
	v_and_or_b32 v4, v5, s41, v4
	s_waitcnt lgkmcnt(1)
	v_bfe_u32 v5, v36, 16, 1
	v_add3_u32 v5, v36, v5, s40
	s_waitcnt lgkmcnt(0)
	v_bfe_u32 v6, v38, 16, 1
	v_lshrrev_b32_e32 v5, 16, v5
	v_add3_u32 v6, v38, v6, s40
	v_and_or_b32 v5, v6, s41, v5
	v_or_b32_e32 v6, s2, v48
	v_mul_u32_u24_e32 v6, 0x1600, v6
	v_lshlrev_b32_e32 v12, 1, v6
	v_lshl_add_u64 v[40:41], v[0:1], 0, v[12:13]
	global_store_dwordx4 v[40:41], v[2:5], off
	v_bfe_u32 v6, v39, 16, 1
	v_add3_u32 v6, v39, v6, s40
	v_bfe_u32 v2, v7, 16, 1
	v_add3_u32 v2, v7, v2, s40
	v_bfe_u32 v3, v27, 16, 1
	v_lshrrev_b32_e32 v2, 16, v2
	v_add3_u32 v3, v27, v3, s40
	v_and_or_b32 v2, v3, s41, v2
	v_bfe_u32 v3, v29, 16, 1
	v_add3_u32 v3, v29, v3, s40
	v_bfe_u32 v4, v31, 16, 1
	v_lshrrev_b32_e32 v3, 16, v3
	v_add3_u32 v4, v31, v4, s40
	v_and_or_b32 v3, v4, s41, v3
	v_bfe_u32 v4, v33, 16, 1
	v_add3_u32 v4, v33, v4, s40
	v_bfe_u32 v5, v35, 16, 1
	v_lshrrev_b32_e32 v4, 16, v4
	v_add3_u32 v5, v35, v5, s40
	v_and_or_b32 v4, v5, s41, v4
	v_bfe_u32 v5, v37, 16, 1
	v_add3_u32 v5, v37, v5, s40
	v_lshrrev_b32_e32 v5, 16, v5
	v_and_or_b32 v5, v6, s41, v5
	v_or_b32_e32 v6, s2, v49
	v_mul_u32_u24_e32 v12, 0x1600, v6
	v_lshlrev_b32_e32 v12, 1, v12
	ds_read2_b32 v[6:7], v46 offset0:32 offset1:40
	v_lshl_add_u64 v[26:27], v[0:1], 0, v[12:13]
	global_store_dwordx4 v[26:27], v[2:5], off
	ds_read2_b32 v[26:27], v46 offset0:97 offset1:105
	ds_read2_b32 v[28:29], v46 offset0:162 offset1:170
	ds_read2_b32 v[30:31], v46 offset0:227 offset1:235
	s_waitcnt lgkmcnt(3)
	v_bfe_u32 v2, v6, 16, 1
	v_add3_u32 v2, v6, v2, s40
	s_waitcnt lgkmcnt(2)
	v_bfe_u32 v3, v26, 16, 1
	ds_read2_b32 v[32:33], v42 offset0:36 offset1:44
	v_lshrrev_b32_e32 v2, 16, v2
	v_add3_u32 v3, v26, v3, s40
	ds_read2_b32 v[34:35], v42 offset0:101 offset1:109
	v_and_or_b32 v2, v3, s41, v2
	s_waitcnt lgkmcnt(3)
	v_bfe_u32 v3, v28, 16, 1
	v_add3_u32 v3, v28, v3, s40
	s_waitcnt lgkmcnt(2)
	v_bfe_u32 v4, v30, 16, 1
	ds_read2_b32 v[36:37], v42 offset0:166 offset1:174
	v_lshrrev_b32_e32 v3, 16, v3
	v_add3_u32 v4, v30, v4, s40
	ds_read2_b32 v[38:39], v42 offset0:231 offset1:239
	v_and_or_b32 v3, v4, s41, v3
	s_waitcnt lgkmcnt(3)
	v_bfe_u32 v4, v32, 16, 1
	v_add3_u32 v4, v32, v4, s40
	s_waitcnt lgkmcnt(2)
	v_bfe_u32 v5, v34, 16, 1
	v_lshrrev_b32_e32 v4, 16, v4
	v_add3_u32 v5, v34, v5, s40
	v_and_or_b32 v4, v5, s41, v4
	s_waitcnt lgkmcnt(1)
	v_bfe_u32 v5, v36, 16, 1
	v_add3_u32 v5, v36, v5, s40
	s_waitcnt lgkmcnt(0)
	v_bfe_u32 v6, v38, 16, 1
	v_lshrrev_b32_e32 v5, 16, v5
	v_add3_u32 v6, v38, v6, s40
	v_and_or_b32 v5, v6, s41, v5
	v_or_b32_e32 v6, s2, v50
	v_mul_u32_u24_e32 v6, 0x1600, v6
	v_lshlrev_b32_e32 v12, 1, v6
	v_lshl_add_u64 v[40:41], v[0:1], 0, v[12:13]
	global_store_dwordx4 v[40:41], v[2:5], off
	v_bfe_u32 v6, v39, 16, 1
	v_add3_u32 v6, v39, v6, s40
	v_bfe_u32 v2, v7, 16, 1
	v_add3_u32 v2, v7, v2, s40
	v_bfe_u32 v3, v27, 16, 1
	v_lshrrev_b32_e32 v2, 16, v2
	v_add3_u32 v3, v27, v3, s40
	v_and_or_b32 v2, v3, s41, v2
	v_bfe_u32 v3, v29, 16, 1
	v_add3_u32 v3, v29, v3, s40
	v_bfe_u32 v4, v31, 16, 1
	v_lshrrev_b32_e32 v3, 16, v3
	v_add3_u32 v4, v31, v4, s40
	v_and_or_b32 v3, v4, s41, v3
	v_bfe_u32 v4, v33, 16, 1
	v_add3_u32 v4, v33, v4, s40
	v_bfe_u32 v5, v35, 16, 1
	v_lshrrev_b32_e32 v4, 16, v4
	v_add3_u32 v5, v35, v5, s40
	v_and_or_b32 v4, v5, s41, v4
	v_bfe_u32 v5, v37, 16, 1
	v_add3_u32 v5, v37, v5, s40
	v_lshrrev_b32_e32 v5, 16, v5
	v_and_or_b32 v5, v6, s41, v5
	v_or_b32_e32 v6, s2, v51
	v_mul_u32_u24_e32 v12, 0x1600, v6
	v_lshlrev_b32_e32 v12, 1, v12
	ds_read2_b32 v[6:7], v46 offset0:48 offset1:56
	v_lshl_add_u64 v[26:27], v[0:1], 0, v[12:13]
	global_store_dwordx4 v[26:27], v[2:5], off
	ds_read2_b32 v[26:27], v46 offset0:113 offset1:121
	ds_read2_b32 v[28:29], v46 offset0:178 offset1:186
	ds_read2_b32 v[30:31], v46 offset0:243 offset1:251
	s_waitcnt lgkmcnt(3)
	v_bfe_u32 v2, v6, 16, 1
	v_add3_u32 v2, v6, v2, s40
	s_waitcnt lgkmcnt(2)
	v_bfe_u32 v3, v26, 16, 1
	ds_read2_b32 v[32:33], v42 offset0:52 offset1:60
	v_lshrrev_b32_e32 v2, 16, v2
	v_add3_u32 v3, v26, v3, s40
	ds_read2_b32 v[34:35], v42 offset0:117 offset1:125
	v_and_or_b32 v2, v3, s41, v2
	s_waitcnt lgkmcnt(3)
	v_bfe_u32 v3, v28, 16, 1
	v_add3_u32 v3, v28, v3, s40
	s_waitcnt lgkmcnt(2)
	v_bfe_u32 v4, v30, 16, 1
	ds_read2_b32 v[36:37], v42 offset0:182 offset1:190
	v_lshrrev_b32_e32 v3, 16, v3
	v_add3_u32 v4, v30, v4, s40
	ds_read2_b32 v[38:39], v42 offset0:247 offset1:255
	v_and_or_b32 v3, v4, s41, v3
	s_waitcnt lgkmcnt(3)
	v_bfe_u32 v4, v32, 16, 1
	v_add3_u32 v4, v32, v4, s40
	s_waitcnt lgkmcnt(2)
	v_bfe_u32 v5, v34, 16, 1
	v_lshrrev_b32_e32 v4, 16, v4
	v_add3_u32 v5, v34, v5, s40
	v_and_or_b32 v4, v5, s41, v4
	s_waitcnt lgkmcnt(1)
	v_bfe_u32 v5, v36, 16, 1
	v_add3_u32 v5, v36, v5, s40
	s_waitcnt lgkmcnt(0)
	v_bfe_u32 v6, v38, 16, 1
	v_lshrrev_b32_e32 v5, 16, v5
	v_add3_u32 v6, v38, v6, s40
	v_and_or_b32 v5, v6, s41, v5
	v_or_b32_e32 v6, s2, v52
	v_mul_u32_u24_e32 v6, 0x1600, v6
	v_lshlrev_b32_e32 v12, 1, v6
	v_lshl_add_u64 v[40:41], v[0:1], 0, v[12:13]
	global_store_dwordx4 v[40:41], v[2:5], off
	v_bfe_u32 v6, v39, 16, 1
	v_add3_u32 v6, v39, v6, s40
	v_bfe_u32 v2, v7, 16, 1
	v_add3_u32 v2, v7, v2, s40
	v_bfe_u32 v3, v27, 16, 1
	v_lshrrev_b32_e32 v2, 16, v2
	v_add3_u32 v3, v27, v3, s40
	v_and_or_b32 v2, v3, s41, v2
	v_bfe_u32 v3, v29, 16, 1
	v_add3_u32 v3, v29, v3, s40
	v_bfe_u32 v4, v31, 16, 1
	v_lshrrev_b32_e32 v3, 16, v3
	v_add3_u32 v4, v31, v4, s40
	v_and_or_b32 v3, v4, s41, v3
	v_bfe_u32 v4, v33, 16, 1
	v_add3_u32 v4, v33, v4, s40
	v_bfe_u32 v5, v35, 16, 1
	v_lshrrev_b32_e32 v4, 16, v4
	v_add3_u32 v5, v35, v5, s40
	v_and_or_b32 v4, v5, s41, v4
	v_bfe_u32 v5, v37, 16, 1
	v_add3_u32 v5, v37, v5, s40
	v_lshrrev_b32_e32 v5, 16, v5
	v_and_or_b32 v5, v6, s41, v5
	v_or_b32_e32 v6, s2, v53
	v_mul_u32_u24_e32 v6, 0x1600, v6
	v_lshlrev_b32_e32 v12, 1, v6
	v_lshl_add_u64 v[0:1], v[0:1], 0, v[12:13]
	global_store_dwordx4 v[0:1], v[2:5], off
	s_waitcnt lgkmcnt(0)
	s_mov_b64 s[2:3], 0

.LBB0_958:
	v_lshl_add_u64 v[74:75], v[22:23], 0, s[2:3]
	v_lshl_add_u64 v[76:77], v[20:21], 0, s[2:3]
	v_lshl_add_u64 v[78:79], v[18:19], 0, s[2:3]
	v_lshl_add_u64 v[80:81], v[16:17], 0, s[2:3]
	v_lshl_add_u64 v[82:83], v[6:7], 0, s[2:3]
	v_lshl_add_u64 v[84:85], v[4:5], 0, s[2:3]
	v_lshl_add_u64 v[86:87], v[2:3], 0, s[2:3]
	v_lshl_add_u64 v[88:89], v[0:1], 0, s[2:3]
	global_load_dwordx4 v[42:45], v[74:75], off
	global_load_dwordx4 v[46:49], v[76:77], off
	global_load_dwordx4 v[50:53], v[78:79], off
	global_load_dwordx4 v[54:57], v[80:81], off
	global_load_dwordx4 v[58:61], v[82:83], off
	global_load_dwordx4 v[62:65], v[84:85], off
	global_load_dwordx4 v[66:69], v[86:87], off
	global_load_dwordx4 v[70:73], v[88:89], off
	s_add_u32 s2, s2, 0x40000
	s_addc_u32 s3, s3, 0
	v_lshl_add_u64 v[74:75], v[22:23], 0, s[2:3]
	v_lshl_add_u64 v[76:77], v[20:21], 0, s[2:3]
	v_lshl_add_u64 v[78:79], v[18:19], 0, s[2:3]
	v_lshl_add_u64 v[80:81], v[16:17], 0, s[2:3]
	v_lshl_add_u64 v[82:83], v[6:7], 0, s[2:3]
	v_lshl_add_u64 v[84:85], v[4:5], 0, s[2:3]
	v_lshl_add_u64 v[86:87], v[2:3], 0, s[2:3]
	v_lshl_add_u64 v[88:89], v[0:1], 0, s[2:3]
	global_load_dwordx4 v[144:147], v[74:75], off
	global_load_dwordx4 v[148:151], v[76:77], off
	global_load_dwordx4 v[152:155], v[78:79], off
	global_load_dwordx4 v[156:159], v[80:81], off
	global_load_dwordx4 v[160:163], v[82:83], off
	global_load_dwordx4 v[164:167], v[84:85], off
	global_load_dwordx4 v[168:171], v[86:87], off
	global_load_dwordx4 v[172:175], v[88:89], off
	v_add_u32_e32 v74, 0x410, v10
	v_add_u32_e32 v75, 0x418, v10
	v_add_u32_e32 v76, 0x820, v10
	v_add_u32_e32 v77, 0x828, v10
	v_add_u32_e32 v78, 0xc30, v10
	v_add_u32_e32 v79, 0xc38, v10
	v_add_u32_e32 v80, 0x1040, v10
	v_add_u32_e32 v81, 0x1048, v10
	v_add_u32_e32 v82, 0x1450, v10
	v_add_u32_e32 v83, 0x1458, v10
	v_add_u32_e32 v84, 0x1860, v10
	v_add_u32_e32 v85, 0x1868, v10
	v_add_u32_e32 v86, 0x1c70, v10
	v_add_u32_e32 v87, 0x1c78, v10
	s_waitcnt vmcnt(15)
	ds_write2_b32 v10, v42, v43 offset1:1
	ds_write2_b32 v10, v44, v45 offset0:2 offset1:3
	s_waitcnt vmcnt(14)
	ds_write2_b32 v74, v46, v47 offset1:1
	ds_write2_b32 v75, v48, v49 offset1:1
	s_waitcnt vmcnt(13)
	ds_write2_b32 v76, v50, v51 offset1:1
	ds_write2_b32 v77, v52, v53 offset1:1
	s_waitcnt vmcnt(12)
	ds_write2_b32 v78, v54, v55 offset1:1
	ds_write2_b32 v79, v56, v57 offset1:1
	s_waitcnt vmcnt(11)
	ds_write2_b32 v80, v58, v59 offset1:1
	ds_write2_b32 v81, v60, v61 offset1:1
	s_waitcnt vmcnt(10)
	ds_write2_b32 v82, v62, v63 offset1:1
	ds_write2_b32 v83, v64, v65 offset1:1
	s_waitcnt vmcnt(9)
	ds_write2_b32 v84, v66, v67 offset1:1
	ds_write2_b32 v85, v68, v69 offset1:1
	s_waitcnt vmcnt(8)
	ds_write2_b32 v86, v70, v71 offset1:1
	ds_write2_b32 v87, v72, v73 offset1:1
	v_add_u32_e32 v10, 0x2080, v10
	v_add_u32_e32 v74, 0x410, v10
	v_add_u32_e32 v75, 0x418, v10
	v_add_u32_e32 v76, 0x820, v10
	v_add_u32_e32 v77, 0x828, v10
	v_add_u32_e32 v78, 0xc30, v10
	v_add_u32_e32 v79, 0xc38, v10
	v_add_u32_e32 v80, 0x1040, v10
	v_add_u32_e32 v81, 0x1048, v10
	v_add_u32_e32 v82, 0x1450, v10
	v_add_u32_e32 v83, 0x1458, v10
	v_add_u32_e32 v84, 0x1860, v10
	v_add_u32_e32 v85, 0x1868, v10
	v_add_u32_e32 v86, 0x1c70, v10
	v_add_u32_e32 v87, 0x1c78, v10
	s_waitcnt vmcnt(7)
	ds_write2_b32 v10, v144, v145 offset1:1
	ds_write2_b32 v10, v146, v147 offset0:2 offset1:3
	s_waitcnt vmcnt(6)
	ds_write2_b32 v74, v148, v149 offset1:1
	ds_write2_b32 v75, v150, v151 offset1:1
	s_waitcnt vmcnt(5)
	ds_write2_b32 v76, v152, v153 offset1:1
	ds_write2_b32 v77, v154, v155 offset1:1
	s_waitcnt vmcnt(4)
	ds_write2_b32 v78, v156, v157 offset1:1
	ds_write2_b32 v79, v158, v159 offset1:1
	s_waitcnt vmcnt(3)
	ds_write2_b32 v80, v160, v161 offset1:1
	ds_write2_b32 v81, v162, v163 offset1:1
	s_waitcnt vmcnt(2)
	ds_write2_b32 v82, v164, v165 offset1:1
	ds_write2_b32 v83, v166, v167 offset1:1
	s_waitcnt vmcnt(1)
	ds_write2_b32 v84, v168, v169 offset1:1
	ds_write2_b32 v85, v170, v171 offset1:1
	s_waitcnt vmcnt(0)
	ds_write2_b32 v86, v172, v173 offset1:1
	ds_write2_b32 v87, v174, v175 offset1:1
	v_add_u32_e32 v10, 0x2080, v10
	s_add_u32 s2, s2, 0x40000
	s_addc_u32 s3, s3, 0
	s_waitcnt lgkmcnt(0)
	ds_read2_b32 v[6:7], v25 offset1:8
	ds_read2_b32 v[16:17], v25 offset0:65 offset1:73
	ds_read2_b32 v[18:19], v25 offset0:130 offset1:138
	ds_read2_b32 v[20:21], v25 offset0:195 offset1:203
	v_add_u32_e32 v50, 0x400, v25
	s_waitcnt lgkmcnt(3)
	v_bfe_u32 v2, v6, 16, 1
	v_add3_u32 v2, v6, v2, s25
	s_waitcnt lgkmcnt(2)
	v_bfe_u32 v3, v16, 16, 1
	ds_read2_b32 v[22:23], v50 offset0:4 offset1:12
	v_lshrrev_b32_e32 v2, 16, v2
	v_add3_u32 v3, v16, v3, s25
	ds_read2_b32 v[42:43], v50 offset0:69 offset1:77
	v_and_or_b32 v2, v3, s26, v2
	s_waitcnt lgkmcnt(3)
	v_bfe_u32 v3, v18, 16, 1
	v_add3_u32 v3, v18, v3, s25
	s_waitcnt lgkmcnt(2)
	v_bfe_u32 v4, v20, 16, 1
	ds_read2_b32 v[44:45], v50 offset0:134 offset1:142
	v_lshrrev_b32_e32 v3, 16, v3
	v_add3_u32 v4, v20, v4, s25
	ds_read2_b32 v[46:47], v50 offset0:199 offset1:207
	v_and_or_b32 v3, v4, s26, v3
	s_waitcnt lgkmcnt(3)
	v_bfe_u32 v4, v22, 16, 1
	v_add3_u32 v4, v22, v4, s25
	s_waitcnt lgkmcnt(2)
	v_bfe_u32 v5, v42, 16, 1
	v_lshrrev_b32_e32 v4, 16, v4
	v_add3_u32 v5, v42, v5, s25
	v_and_or_b32 v4, v5, s26, v4
	s_waitcnt lgkmcnt(1)
	v_bfe_u32 v5, v44, 16, 1
	s_lshl_b32 s2, s30, 6
	v_add3_u32 v5, v44, v5, s25
	s_waitcnt lgkmcnt(0)
	v_bfe_u32 v6, v46, 16, 1
	s_and_b32 s2, s2, 0x7c0
	s_lshl_b32 s3, s30, 1
	v_lshrrev_b32_e32 v5, 16, v5
	v_add3_u32 v6, v46, v6, s25
	s_and_b32 s3, s3, 0x7fffffc0
	v_and_or_b32 v5, v6, s26, v5
	v_or_b32_e32 v6, s2, v24
	s_add_i32 s4, s3, 0xffffd400
	v_mul_u32_u24_e32 v6, 0x1600, v6
	v_lshl_add_u64 v[0:1], s[4:5], 1, v[12:13]
	v_lshlrev_b32_e32 v10, 1, v6
	v_lshl_add_u64 v[48:49], v[0:1], 0, v[10:11]
	global_store_dwordx4 v[48:49], v[2:5], off
	v_bfe_u32 v6, v47, 16, 1
	v_add3_u32 v6, v47, v6, s25
	v_bfe_u32 v2, v7, 16, 1
	v_add3_u32 v2, v7, v2, s25
	v_bfe_u32 v3, v17, 16, 1
	v_lshrrev_b32_e32 v2, 16, v2
	v_add3_u32 v3, v17, v3, s25
	v_and_or_b32 v2, v3, s26, v2
	v_bfe_u32 v3, v19, 16, 1
	v_add3_u32 v3, v19, v3, s25
	v_bfe_u32 v4, v21, 16, 1
	v_lshrrev_b32_e32 v3, 16, v3
	v_add3_u32 v4, v21, v4, s25
	v_and_or_b32 v3, v4, s26, v3
	v_bfe_u32 v4, v23, 16, 1
	v_add3_u32 v4, v23, v4, s25
	v_bfe_u32 v5, v43, 16, 1
	v_lshrrev_b32_e32 v4, 16, v4
	v_add3_u32 v5, v43, v5, s25
	v_and_or_b32 v4, v5, s26, v4
	v_bfe_u32 v5, v45, 16, 1
	v_add3_u32 v5, v45, v5, s25
	v_lshrrev_b32_e32 v5, 16, v5
	v_and_or_b32 v5, v6, s26, v5
	v_or_b32_e32 v6, s2, v26
	v_mul_u32_u24_e32 v10, 0x1600, v6
	v_lshlrev_b32_e32 v10, 1, v10
	ds_read2_b32 v[6:7], v25 offset0:16 offset1:24
	v_lshl_add_u64 v[16:17], v[0:1], 0, v[10:11]
	global_store_dwordx4 v[16:17], v[2:5], off
	ds_read2_b32 v[16:17], v25 offset0:81 offset1:89
	ds_read2_b32 v[18:19], v25 offset0:146 offset1:154
	ds_read2_b32 v[20:21], v25 offset0:211 offset1:219
	s_waitcnt lgkmcnt(3)
	v_bfe_u32 v2, v6, 16, 1
	v_add3_u32 v2, v6, v2, s25
	s_waitcnt lgkmcnt(2)
	v_bfe_u32 v3, v16, 16, 1
	ds_read2_b32 v[22:23], v50 offset0:20 offset1:28
	v_lshrrev_b32_e32 v2, 16, v2
	v_add3_u32 v3, v16, v3, s25
	ds_read2_b32 v[42:43], v50 offset0:85 offset1:93
	v_and_or_b32 v2, v3, s26, v2
	s_waitcnt lgkmcnt(3)
	v_bfe_u32 v3, v18, 16, 1
	v_add3_u32 v3, v18, v3, s25
	s_waitcnt lgkmcnt(2)
	v_bfe_u32 v4, v20, 16, 1
	ds_read2_b32 v[44:45], v50 offset0:150 offset1:158
	v_lshrrev_b32_e32 v3, 16, v3
	v_add3_u32 v4, v20, v4, s25
	ds_read2_b32 v[46:47], v50 offset0:215 offset1:223
	v_and_or_b32 v3, v4, s26, v3
	s_waitcnt lgkmcnt(3)
	v_bfe_u32 v4, v22, 16, 1
	v_add3_u32 v4, v22, v4, s25
	s_waitcnt lgkmcnt(2)
	v_bfe_u32 v5, v42, 16, 1
	v_lshrrev_b32_e32 v4, 16, v4
	v_add3_u32 v5, v42, v5, s25
	v_and_or_b32 v4, v5, s26, v4
	s_waitcnt lgkmcnt(1)
	v_bfe_u32 v5, v44, 16, 1
	v_add3_u32 v5, v44, v5, s25
	s_waitcnt lgkmcnt(0)
	v_bfe_u32 v6, v46, 16, 1
	v_lshrrev_b32_e32 v5, 16, v5
	v_add3_u32 v6, v46, v6, s25
	v_and_or_b32 v5, v6, s26, v5
	v_or_b32_e32 v6, s2, v27
	v_mul_u32_u24_e32 v6, 0x1600, v6
	v_lshlrev_b32_e32 v10, 1, v6
	v_lshl_add_u64 v[48:49], v[0:1], 0, v[10:11]
	global_store_dwordx4 v[48:49], v[2:5], off
	v_bfe_u32 v6, v47, 16, 1
	v_add3_u32 v6, v47, v6, s25
	v_bfe_u32 v2, v7, 16, 1
	v_add3_u32 v2, v7, v2, s25
	v_bfe_u32 v3, v17, 16, 1
	v_lshrrev_b32_e32 v2, 16, v2
	v_add3_u32 v3, v17, v3, s25
	v_and_or_b32 v2, v3, s26, v2
	v_bfe_u32 v3, v19, 16, 1
	v_add3_u32 v3, v19, v3, s25
	v_bfe_u32 v4, v21, 16, 1
	v_lshrrev_b32_e32 v3, 16, v3
	v_add3_u32 v4, v21, v4, s25
	v_and_or_b32 v3, v4, s26, v3
	v_bfe_u32 v4, v23, 16, 1
	v_add3_u32 v4, v23, v4, s25
	v_bfe_u32 v5, v43, 16, 1
	v_lshrrev_b32_e32 v4, 16, v4
	v_add3_u32 v5, v43, v5, s25
	v_and_or_b32 v4, v5, s26, v4
	v_bfe_u32 v5, v45, 16, 1
	v_add3_u32 v5, v45, v5, s25
	v_lshrrev_b32_e32 v5, 16, v5
	v_and_or_b32 v5, v6, s26, v5
	v_or_b32_e32 v6, s2, v28
	v_mul_u32_u24_e32 v10, 0x1600, v6
	v_lshlrev_b32_e32 v10, 1, v10
	ds_read2_b32 v[6:7], v25 offset0:32 offset1:40
	v_lshl_add_u64 v[16:17], v[0:1], 0, v[10:11]
	global_store_dwordx4 v[16:17], v[2:5], off
	ds_read2_b32 v[16:17], v25 offset0:97 offset1:105
	ds_read2_b32 v[18:19], v25 offset0:162 offset1:170
	ds_read2_b32 v[20:21], v25 offset0:227 offset1:235
	s_waitcnt lgkmcnt(3)
	v_bfe_u32 v2, v6, 16, 1
	v_add3_u32 v2, v6, v2, s25
	s_waitcnt lgkmcnt(2)
	v_bfe_u32 v3, v16, 16, 1
	ds_read2_b32 v[22:23], v50 offset0:36 offset1:44
	v_lshrrev_b32_e32 v2, 16, v2
	v_add3_u32 v3, v16, v3, s25
	ds_read2_b32 v[42:43], v50 offset0:101 offset1:109
	v_and_or_b32 v2, v3, s26, v2
	s_waitcnt lgkmcnt(3)
	v_bfe_u32 v3, v18, 16, 1
	v_add3_u32 v3, v18, v3, s25
	s_waitcnt lgkmcnt(2)
	v_bfe_u32 v4, v20, 16, 1
	ds_read2_b32 v[44:45], v50 offset0:166 offset1:174
	v_lshrrev_b32_e32 v3, 16, v3
	v_add3_u32 v4, v20, v4, s25
	ds_read2_b32 v[46:47], v50 offset0:231 offset1:239
	v_and_or_b32 v3, v4, s26, v3
	s_waitcnt lgkmcnt(3)
	v_bfe_u32 v4, v22, 16, 1
	v_add3_u32 v4, v22, v4, s25
	s_waitcnt lgkmcnt(2)
	v_bfe_u32 v5, v42, 16, 1
	v_lshrrev_b32_e32 v4, 16, v4
	v_add3_u32 v5, v42, v5, s25
	v_and_or_b32 v4, v5, s26, v4
	s_waitcnt lgkmcnt(1)
	v_bfe_u32 v5, v44, 16, 1
	v_add3_u32 v5, v44, v5, s25
	s_waitcnt lgkmcnt(0)
	v_bfe_u32 v6, v46, 16, 1
	v_lshrrev_b32_e32 v5, 16, v5
	v_add3_u32 v6, v46, v6, s25
	v_and_or_b32 v5, v6, s26, v5
	v_or_b32_e32 v6, s2, v29
	v_mul_u32_u24_e32 v6, 0x1600, v6
	v_lshlrev_b32_e32 v10, 1, v6
	v_lshl_add_u64 v[48:49], v[0:1], 0, v[10:11]
	global_store_dwordx4 v[48:49], v[2:5], off
	v_bfe_u32 v6, v47, 16, 1
	v_add3_u32 v6, v47, v6, s25
	v_bfe_u32 v2, v7, 16, 1
	v_add3_u32 v2, v7, v2, s25
	v_bfe_u32 v3, v17, 16, 1
	v_lshrrev_b32_e32 v2, 16, v2
	v_add3_u32 v3, v17, v3, s25
	v_and_or_b32 v2, v3, s26, v2
	v_bfe_u32 v3, v19, 16, 1
	v_add3_u32 v3, v19, v3, s25
	v_bfe_u32 v4, v21, 16, 1
	v_lshrrev_b32_e32 v3, 16, v3
	v_add3_u32 v4, v21, v4, s25
	v_and_or_b32 v3, v4, s26, v3
	v_bfe_u32 v4, v23, 16, 1
	v_add3_u32 v4, v23, v4, s25
	v_bfe_u32 v5, v43, 16, 1
	v_lshrrev_b32_e32 v4, 16, v4
	v_add3_u32 v5, v43, v5, s25
	v_and_or_b32 v4, v5, s26, v4
	v_bfe_u32 v5, v45, 16, 1
	v_add3_u32 v5, v45, v5, s25
	v_lshrrev_b32_e32 v5, 16, v5
	v_and_or_b32 v5, v6, s26, v5
	v_or_b32_e32 v6, s2, v30
	v_mul_u32_u24_e32 v10, 0x1600, v6
	v_lshlrev_b32_e32 v10, 1, v10
	ds_read2_b32 v[6:7], v25 offset0:48 offset1:56
	v_lshl_add_u64 v[16:17], v[0:1], 0, v[10:11]
	global_store_dwordx4 v[16:17], v[2:5], off
	ds_read2_b32 v[16:17], v25 offset0:113 offset1:121
	ds_read2_b32 v[18:19], v25 offset0:178 offset1:186
	ds_read2_b32 v[20:21], v25 offset0:243 offset1:251
	s_waitcnt lgkmcnt(3)
	v_bfe_u32 v2, v6, 16, 1
	v_add3_u32 v2, v6, v2, s25
	s_waitcnt lgkmcnt(2)
	v_bfe_u32 v3, v16, 16, 1
	ds_read2_b32 v[22:23], v50 offset0:52 offset1:60
	v_lshrrev_b32_e32 v2, 16, v2
	v_add3_u32 v3, v16, v3, s25
	ds_read2_b32 v[42:43], v50 offset0:117 offset1:125
	v_and_or_b32 v2, v3, s26, v2
	s_waitcnt lgkmcnt(3)
	v_bfe_u32 v3, v18, 16, 1
	v_add3_u32 v3, v18, v3, s25
	s_waitcnt lgkmcnt(2)
	v_bfe_u32 v4, v20, 16, 1
	ds_read2_b32 v[44:45], v50 offset0:182 offset1:190
	v_lshrrev_b32_e32 v3, 16, v3
	v_add3_u32 v4, v20, v4, s25
	ds_read2_b32 v[46:47], v50 offset0:247 offset1:255
	v_and_or_b32 v3, v4, s26, v3
	s_waitcnt lgkmcnt(3)
	v_bfe_u32 v4, v22, 16, 1
	v_add3_u32 v4, v22, v4, s25
	s_waitcnt lgkmcnt(2)
	v_bfe_u32 v5, v42, 16, 1
	v_lshrrev_b32_e32 v4, 16, v4
	v_add3_u32 v5, v42, v5, s25
	v_and_or_b32 v4, v5, s26, v4
	s_waitcnt lgkmcnt(1)
	v_bfe_u32 v5, v44, 16, 1
	v_add3_u32 v5, v44, v5, s25
	s_waitcnt lgkmcnt(0)
	v_bfe_u32 v6, v46, 16, 1
	v_lshrrev_b32_e32 v5, 16, v5
	v_add3_u32 v6, v46, v6, s25
	v_and_or_b32 v5, v6, s26, v5
	v_or_b32_e32 v6, s2, v31
	v_mul_u32_u24_e32 v6, 0x1600, v6
	v_lshlrev_b32_e32 v10, 1, v6
	v_lshl_add_u64 v[48:49], v[0:1], 0, v[10:11]
	global_store_dwordx4 v[48:49], v[2:5], off
	v_bfe_u32 v6, v47, 16, 1
	v_add3_u32 v6, v47, v6, s25
	v_bfe_u32 v2, v7, 16, 1
	v_add3_u32 v2, v7, v2, s25
	v_bfe_u32 v3, v17, 16, 1
	v_lshrrev_b32_e32 v2, 16, v2
	v_add3_u32 v3, v17, v3, s25
	v_and_or_b32 v2, v3, s26, v2
	v_bfe_u32 v3, v19, 16, 1
	v_add3_u32 v3, v19, v3, s25
	v_bfe_u32 v4, v21, 16, 1
	v_lshrrev_b32_e32 v3, 16, v3
	v_add3_u32 v4, v21, v4, s25
	v_and_or_b32 v3, v4, s26, v3
	v_bfe_u32 v4, v23, 16, 1
	v_add3_u32 v4, v23, v4, s25
	v_bfe_u32 v5, v43, 16, 1
	v_lshrrev_b32_e32 v4, 16, v4
	v_add3_u32 v5, v43, v5, s25
	v_and_or_b32 v4, v5, s26, v4
	v_bfe_u32 v5, v45, 16, 1
	v_add3_u32 v5, v45, v5, s25
	v_lshrrev_b32_e32 v5, 16, v5
	v_and_or_b32 v5, v6, s26, v5
	v_or_b32_e32 v6, s2, v32
	v_mul_u32_u24_e32 v6, 0x1600, v6
	v_lshlrev_b32_e32 v10, 1, v6
	v_lshl_add_u64 v[0:1], v[0:1], 0, v[10:11]
	global_store_dwordx4 v[0:1], v[2:5], off
	s_waitcnt lgkmcnt(0)
	s_mov_b64 s[2:3], 0
